# P0 work sharing: the weight-conversion waves, once their items are done, stream x rows [25600, 32768) with their own stride; the row waves take rows [0, 25600)
# speedup vs baseline: 1.0085x; 1.0085x over previous
.LBB0_288:
	s_mov_b32 s98, 0x6400
	s_and_b64 vcc, exec, s[4:5]
	s_cbranch_vccz .Lp0_rw
	v_readlane_b32 s0, v243, 6
	s_mul_i32 s24, s33, 3
	s_add_i32 s24, s24, s0
	s_add_i32 s24, s24, 0x63fb
	s_mov_b32 s98, 0x8000
.Lp0_rw:
	s_cmp_ge_i32 s24, s98
	s_cbranch_scc1 .LBB0_349
	v_mbcnt_lo_u32_b32 v2, -1, 0
	v_mbcnt_hi_u32_b32 v2, -1, v2
	v_and_b32_e32 v3, 64, v2
	v_add_u32_e32 v3, 64, v3
	v_xor_b32_e32 v4, 1, v2
	v_cmp_lt_i32_e32 vcc, v4, v3
	s_add_u32 s39, s60, 0x1600000
	s_addc_u32 s65, s61, 0
	v_cndmask_b32_e32 v4, v2, v4, vcc
	v_lshlrev_b32_e32 v138, 2, v4
	v_xor_b32_e32 v4, 2, v2
	v_cmp_lt_i32_e32 vcc, v4, v3
	s_ashr_i32 s25, s24, 31
	s_lshl_b32 s0, s38, 3
	v_cndmask_b32_e32 v4, v2, v4, vcc
	v_lshlrev_b32_e32 v139, 2, v4
	v_xor_b32_e32 v4, 4, v2
	v_cmp_lt_i32_e32 vcc, v4, v3
	s_lshl_b32 s66, s38, 1
	s_lshl_b32 s79, s38, 2
	v_cndmask_b32_e32 v4, v2, v4, vcc
	v_lshlrev_b32_e32 v140, 2, v4
	v_xor_b32_e32 v4, 8, v2
	v_cmp_lt_i32_e32 vcc, v4, v3
	s_lshl_b64 s[10:11], s[24:25], 2
	s_add_u32 s84, s10, 0x1600000
	v_cndmask_b32_e32 v4, v2, v4, vcc
	v_lshlrev_b32_e32 v141, 2, v4
	v_xor_b32_e32 v4, 16, v2
	v_lshlrev_b32_e32 v128, 3, v206
	v_mov_b32_e32 v129, 0
	v_cmp_lt_i32_e32 vcc, v4, v3
	s_addc_u32 s85, s11, 0
	s_ashr_i32 s1, s0, 31
	s_lshl_b64 s[12:13], s[24:25], 11
	v_lshlrev_b32_e32 v0, 4, v206
	v_mov_b32_e32 v1, v129
	v_cndmask_b32_e32 v4, v2, v4, vcc
	s_lshl_b64 s[10:11], s[0:1], 2
	v_or_b32_e32 v134, s12, v128
	v_mov_b32_e32 v135, s13
	s_lshl_b64 s[12:13], s[0:1], 11
	s_lshl_b64 s[22:23], s[24:25], 12
	v_lshl_add_u64 v[132:133], s[8:9], 0, v[0:1]
	v_lshlrev_b32_e32 v142, 2, v4
	v_xor_b32_e32 v4, 32, v2
	s_add_u32 s8, s8, s22
	v_cmp_lt_i32_e32 vcc, v4, v3
	s_addc_u32 s9, s9, s23
	v_lshl_add_u64 v[0:1], s[8:9], 0, v[0:1]
	v_cndmask_b32_e32 v2, v2, v4, vcc
	s_mov_b64 s[8:9], 0xc00
	v_cmp_eq_u32_e64 s[2:3], 0, v206
	v_cmp_ne_u32_e64 s[4:5], 0, v206
	v_lshl_add_u64 v[130:131], s[68:69], 0, v[128:129]
	v_lshlrev_b32_e32 v143, 2, v2
	s_mul_i32 s67, s38, 3
	s_mul_i32 s81, s38, 5
	s_mul_i32 s82, s38, 6
	s_mul_i32 s83, s38, 7
	v_lshl_add_u64 v[136:137], v[0:1], 0, s[8:9]
	s_lshl_b64 s[8:9], s[0:1], 12
	v_mov_b32_e32 v144, 0x358637bd
	s_mov_b32 s1, 0x800000
	s_brev_b32 s25, 64
	s_branch .LBB0_292

.LBB0_291:
	s_add_i32 s24, s24, s0
	s_add_u32 s84, s84, s10
	s_addc_u32 s85, s85, s11
	v_lshl_add_u64 v[134:135], v[134:135], 0, s[12:13]
	s_cmp_lt_i32 s24, s98
	v_lshl_add_u64 v[136:137], v[136:137], 0, s[8:9]
	s_cbranch_scc0 .LBB0_349
.LBB0_292:
	global_load_dwordx4 v[124:127], v[136:137], off offset:-3072 nt
	global_load_dwordx4 v[120:123], v[136:137], off offset:-2048 nt
	global_load_dwordx4 v[116:119], v[136:137], off offset:-1024 nt
	global_load_dwordx4 v[112:115], v[136:137], off nt
	s_add_i32 s72, s38, s24
	s_cmp_lt_i32 s72, s98
	s_cselect_b64 s[74:75], -1, 0
	s_cmp_ge_i32 s72, s98
	s_cbranch_scc1 .LBB0_294
	s_ashr_i32 s73, s72, 31
	s_lshl_b64 s[22:23], s[72:73], 12
	v_lshl_add_u64 v[96:97], v[132:133], 0, s[22:23]
	global_load_dwordx4 v[108:111], v[96:97], off nt
	global_load_dwordx4 v[104:107], v[96:97], off offset:1024 nt
	global_load_dwordx4 v[100:103], v[96:97], off offset:2048 nt
	s_nop 0
	global_load_dwordx4 v[96:99], v[96:97], off offset:3072 nt
.LBB0_294:
	s_add_i32 s54, s66, s24
	s_cmp_lt_i32 s54, s98
	s_cselect_b64 s[70:71], -1, 0
	s_cmp_ge_i32 s54, s98
	s_cbranch_scc1 .LBB0_296
	s_ashr_i32 s55, s54, 31
	s_lshl_b64 s[22:23], s[54:55], 12
	v_lshl_add_u64 v[80:81], v[132:133], 0, s[22:23]
	global_load_dwordx4 v[92:95], v[80:81], off nt
	global_load_dwordx4 v[88:91], v[80:81], off offset:1024 nt
	global_load_dwordx4 v[84:87], v[80:81], off offset:2048 nt
	s_nop 0
	global_load_dwordx4 v[80:83], v[80:81], off offset:3072 nt
.LBB0_296:
	s_add_i32 s46, s67, s24
	s_cmp_lt_i32 s46, s98
	s_cselect_b64 s[48:49], -1, 0
	s_cmp_ge_i32 s46, s98
	s_cbranch_scc1 .LBB0_298
	s_ashr_i32 s47, s46, 31
	s_lshl_b64 s[22:23], s[46:47], 12
	v_lshl_add_u64 v[64:65], v[132:133], 0, s[22:23]
	global_load_dwordx4 v[76:79], v[64:65], off nt
	global_load_dwordx4 v[72:75], v[64:65], off offset:1024 nt
	global_load_dwordx4 v[68:71], v[64:65], off offset:2048 nt
	s_nop 0
	global_load_dwordx4 v[64:67], v[64:65], off offset:3072 nt
.LBB0_298:
	s_add_i32 s42, s79, s24
	s_cmp_lt_i32 s42, s98
	s_cselect_b64 s[44:45], -1, 0
	s_cmp_ge_i32 s42, s98
	s_cbranch_scc1 .LBB0_300
	s_ashr_i32 s43, s42, 31
	s_lshl_b64 s[22:23], s[42:43], 12
	v_lshl_add_u64 v[48:49], v[132:133], 0, s[22:23]
	global_load_dwordx4 v[60:63], v[48:49], off nt
	global_load_dwordx4 v[56:59], v[48:49], off offset:1024 nt
	global_load_dwordx4 v[52:55], v[48:49], off offset:2048 nt
	s_nop 0
	global_load_dwordx4 v[48:51], v[48:49], off offset:3072 nt
.LBB0_300:
	s_add_i32 s34, s81, s24
	s_cmp_lt_i32 s34, s98
	s_cselect_b64 s[36:37], -1, 0
	s_cmp_ge_i32 s34, s98
	s_cbranch_scc1 .LBB0_302
	s_ashr_i32 s35, s34, 31
	s_lshl_b64 s[22:23], s[34:35], 12
	v_lshl_add_u64 v[32:33], v[132:133], 0, s[22:23]
	global_load_dwordx4 v[44:47], v[32:33], off nt
	global_load_dwordx4 v[40:43], v[32:33], off offset:1024 nt
	global_load_dwordx4 v[36:39], v[32:33], off offset:2048 nt
	s_nop 0
	global_load_dwordx4 v[32:35], v[32:33], off offset:3072 nt
.LBB0_302:
	s_add_i32 s28, s82, s24
	s_cmp_lt_i32 s28, s98
	s_cselect_b64 s[30:31], -1, 0
	s_cmp_ge_i32 s28, s98
	s_cbranch_scc1 .LBB0_304
	s_ashr_i32 s29, s28, 31
	s_lshl_b64 s[22:23], s[28:29], 12
	v_lshl_add_u64 v[16:17], v[132:133], 0, s[22:23]
	global_load_dwordx4 v[28:31], v[16:17], off nt
	global_load_dwordx4 v[24:27], v[16:17], off offset:1024 nt
	global_load_dwordx4 v[20:23], v[16:17], off offset:2048 nt
	s_nop 0
	global_load_dwordx4 v[16:19], v[16:17], off offset:3072 nt
.LBB0_304:
	s_add_i32 s22, s83, s24
	s_cmp_lt_i32 s22, s98
	s_cselect_b64 s[26:27], -1, 0
	s_cmp_ge_i32 s22, s98
	s_cbranch_scc1 .LBB0_306
	s_ashr_i32 s23, s22, 31
	s_lshl_b64 s[76:77], s[22:23], 12
	v_lshl_add_u64 v[0:1], v[132:133], 0, s[76:77]
	global_load_dwordx4 v[12:15], v[0:1], off nt
	global_load_dwordx4 v[8:11], v[0:1], off offset:1024 nt
	global_load_dwordx4 v[4:7], v[0:1], off offset:2048 nt
	s_nop 0
	global_load_dwordx4 v[0:3], v[0:1], off offset:3072 nt
